# v76 + input residual-norm phase (P0b): rows dealt per XCD in balanced 17/16-row blocks (XCD x owns rows 4160x..4160x+4159) instead of 17 rows per wave with idle tail waves
# speedup vs baseline: 1.0026x; 1.0026x over previous
.LBB0_96:
	s_lshl_b32 s13, s2, 3
	s_abs_i32 s16, s13
	v_and_b32_e32 v3, 63, v0
	v_cvt_f32_u32_e32 v0, s16
	s_sub_i32 s18, 0, s16
	s_add_i32 s17, s13, 0x81ff
	s_xor_b32 s13, s17, s13
	v_rcp_iflag_f32_e32 v0, v0
	s_abs_i32 s17, s17
	s_ashr_i32 s6, s6, 6
	s_lshl_b32 s3, s3, 3
	v_mul_f32_e32 v0, 0x4f7ffffe, v0
	v_cvt_u32_f32_e32 v0, v0
	s_add_i32 s12, s3, s6
	s_ashr_i32 s13, s13, 31
	v_readlane_b32 s14, v255, 2
	v_readfirstlane_b32 s19, v0
	s_mul_i32 s18, s18, s19
	s_mul_hi_u32 s18, s19, s18
	s_add_i32 s19, s19, s18
	s_mul_hi_u32 s18, s17, s19
	s_mul_i32 s19, s18, s16
	s_sub_i32 s17, s17, s19
	s_add_i32 s19, s18, 1
	s_sub_i32 s20, s17, s16
	s_cmp_ge_u32 s17, s16
	s_cselect_b32 s18, s19, s18
	s_cselect_b32 s17, s20, s17
	s_add_i32 s19, s18, 1
	v_readlane_b32 s15, v255, 3
	s_cmp_ge_u32 s17, s16
	s_mov_b64 s[2:3], s[14:15]
	s_cselect_b32 s16, s19, s18
	s_xor_b32 s16, s16, s13
	s_load_dwordx2 s[6:7], s[2:3], 0x0
	s_mov_b64 s[2:3], s[14:15]
	s_sub_i32 s13, s16, s13
	s_load_dwordx2 s[8:9], s[2:3], 0x8
	s_and_b32 s98, s12, 0xff
	s_lshr_b32 s99, s12, 8
	s_mul_i32 s99, s99, 0x1040
	s_mul_i32 s12, s98, 17
	s_add_i32 s13, s98, 0xffffffc0
	s_lshl_b32 s13, s13, 4
	s_addk_i32 s13, 0x440
	s_cmpk_lt_u32 s98, 64
	s_cselect_b32 s12, s12, s13
	s_cselect_b32 s13, 17, 16
	s_add_i32 s12, s12, s99
	s_add_i32 s20, s12, s13
	s_cmp_lt_i32 s12, s20
	s_mov_b64 s[2:3], s[14:15]
	s_mov_b64 s[10:11], s[14:15]
	s_cselect_b64 s[16:17], -1, 0
	s_cmp_ge_i32 s12, s20
	v_lshlrev_b32_e32 v2, 5, v3
	s_cbranch_scc1 .LBB0_98
	s_add_i32 s13, s12, 0xffff8000
	s_ashr_i32 s18, s12, 31
	s_cmp_lt_i32 s12, 0x8000
	s_cselect_b32 s19, s18, 0
	s_cselect_b32 s18, s12, s13
	s_waitcnt lgkmcnt(0)
	s_cselect_b32 s13, s7, s9
	s_cselect_b32 s21, s6, s8
	s_lshl_b64 s[18:19], s[18:19], 12
	s_add_u32 s18, s21, s18
	s_addc_u32 s19, s13, s19
	global_load_dwordx4 v[74:77], v2, s[18:19] offset:16
	global_load_dwordx4 v[78:81], v2, s[18:19]
	global_load_dwordx4 v[66:69], v2, s[18:19] offset:2064
	global_load_dwordx4 v[70:73], v2, s[18:19] offset:2048
